# also K-split sample GEMMs for QKV and GLU phases (all 9 sample GEMM sites hand-written)
# speedup vs baseline: 1.0004x; 1.0004x over previous
; DI float bflo(unsigned w) { return __uint_as_float(w << 16); }
; DI float bfhi(unsigned w) { return __uint_as_float(w & 0xffff0000u); }
; DI float sigmoidf_(float x) { return __builtin_amdgcn_rcpf(1.0f + __builtin_amdgcn_exp2f(-1.4426950408889634f * x)); }
;     DI void elem(int row, int col, const f32x4 v) const { u32x2 w; w.x = pk2(v[0], v[1]); w.y = pk2(v[2], v[3]); *(u32x2*)(y + (size_t)row * 1024 + col) = w; }
;     DI void elem(int row, int col, const f32x4 v) const { const u32x2 zw = *(const u32x2*)(z + (size_t)row * 512 + col); const f32x4 b = *(const f32x4*)(bglu + col);
;         u32x2 w; w.x = pk2(bflo(zw.x) * sigmoidf_(v[0] + b[0]), bfhi(zw.x) * sigmoidf_(v[1] + b[1])); w.y = pk2(bflo(zw.y) * sigmoidf_(v[2] + b[2]), bfhi(zw.y) * sigmoidf_(v[3] + b[3]));
;         *(u32x2*)(ycat + (size_t)row * 1024 + 512 + col) = w; }
; template <class Epi>
; DI void mini_gemm(const bf16_t* A, int lda, const bf16_t* Bt, int ldb, int K, int N, int acol_per_256, const Epi& E, int bx, int G, int wave, int lane) {
;     const int fr = lane & 15, fq = lane >> 4; const int row = NP + 16 * wave + fr;
;     for (int q = bx; q < N / 16; q += G) {
;         const bf16_t* Arow = A + (size_t)row * lda + ((16 * q) >> 8) * acol_per_256 + 8 * fq;
;         const bf16_t* Brow = Bt + (size_t)(16 * q + fr) * ldb + 8 * fq;
;         const f32x4 acc = mini_acc(Arow, Brow, K);
;         E.elem(row, 16 * q + 4 * fq, acc); }
.LBB0_869:
	s_cmp_lg_u32 s78, 0x100
	s_cbranch_scc1 .Lp5_old_p5
	s_cmpk_gt_u32 s84, 0x7f
	s_cbranch_scc1 .LBB0_872
	v_readlane_b32 s98, v254, 0
	v_readlane_b32 s99, v254, 1
	s_nop 0
	s_load_dwordx2 s[100:101], s[98:99], 0x98
	v_mbcnt_lo_u32_b32 v0, -1, 0
	v_mbcnt_hi_u32_b32 v0, -1, v0
	v_and_b32_e32 v1, 15, v0
	v_lshrrev_b32_e32 v2, 4, v0
	s_and_b32 s0, s84, 7
	s_lshr_b32 s1, s84, 5
	s_lshl_b32 s1, s1, 3
	s_add_i32 s0, s0, s1
	s_bfe_u32 s1, s84, 0x20003
	s_lshl_b32 s1, s1, 1
	s_lshr_b32 s2, s87, 2
	s_add_i32 s1, s1, s2
	s_lshl_b32 s1, s1, 4
	s_add_i32 s1, s1, 0x8000
	v_add_u32_e32 v3, s1, v1
	s_lshl_b32 s1, s0, 4
	v_add_u32_e32 v4, s1, v1
	s_and_b32 s32, s87, 3
	s_lshl_b32 s32, s32, 8
	v_lshl_add_u32 v6, v2, 4, s32
	v_mov_b32_e32 v7, 0
	s_add_u32 s98, s90, 0x1fa00000
	s_addc_u32 s99, s91, 0
	s_movk_i32 s2, 0x400
	v_lshl_add_u64 v[8:9], s[98:99], 0, v[6:7]
	v_mad_u64_u32 v[8:9], vcc, v3, s2, v[8:9]
	s_add_u32 s98, s90, 0x400000
	s_addc_u32 s99, s91, 0
	v_lshl_add_u64 v[10:11], s[98:99], 0, v[6:7]
	v_mad_u64_u32 v[10:11], vcc, v4, s2, v[10:11]
	global_load_dwordx4 v[20:23], v[8:9], off
	global_load_dwordx4 v[36:39], v[10:11], off
	global_load_dwordx4 v[24:27], v[8:9], off offset:64
	global_load_dwordx4 v[40:43], v[10:11], off offset:64
	global_load_dwordx4 v[28:31], v[8:9], off offset:128
	global_load_dwordx4 v[44:47], v[10:11], off offset:128
	global_load_dwordx4 v[32:35], v[8:9], off offset:192
	global_load_dwordx4 v[48:51], v[10:11], off offset:192
	s_lshl_b32 s1, s0, 4
	v_lshl_add_u32 v12, v2, 2, s1
	v_lshlrev_b32_e32 v14, 1, v12
	v_mov_b32_e32 v15, 0
	s_add_u32 s98, s90, 0x1fa00000
	s_addc_u32 s99, s91, 0
	v_lshl_add_u64 v[16:17], s[98:99], 0, v[14:15]
	v_mad_u64_u32 v[16:17], vcc, v3, s2, v[16:17]
	global_load_dwordx2 v[68:69], v[16:17], off
	v_lshlrev_b32_e32 v18, 2, v12
	s_waitcnt lgkmcnt(0)
	global_load_dwordx4 v[72:75], v18, s[100:101]
	s_add_u32 s98, s90, 0x21b00400
	s_addc_u32 s99, s91, 0
	s_movk_i32 s2, 0x800
	v_lshl_add_u64 v[76:77], s[98:99], 0, v[14:15]
	v_mad_u64_u32 v[76:77], vcc, v3, s2, v[76:77]
	s_lshl_b32 s1, s87, 10
	v_lshl_add_u32 v13, v0, 4, s1
	s_waitcnt vmcnt(8)
	v_mfma_f32_16x16x32_bf16 v[52:55], v[36:39], v[20:23], 0
	s_waitcnt vmcnt(6)
	v_mfma_f32_16x16x32_bf16 v[52:55], v[40:43], v[24:27], v[52:55]
	s_waitcnt vmcnt(4)
	v_mfma_f32_16x16x32_bf16 v[52:55], v[44:47], v[28:31], v[52:55]
	s_waitcnt vmcnt(2)
	v_mfma_f32_16x16x32_bf16 v[52:55], v[48:51], v[32:35], v[52:55]
	s_nop 7
	s_nop 1
	ds_write_b128 v13, v[52:55]
	s_waitcnt lgkmcnt(0)
	s_barrier
	s_and_b32 s32, s87, 3
	s_cmp_lg_u32 s32, 0
	s_cbranch_scc1 .Lp5_done_p5
	ds_read_b128 v[56:59], v13 offset:1024
	ds_read_b128 v[60:63], v13 offset:2048
	ds_read_b128 v[64:67], v13 offset:3072
	s_waitcnt vmcnt(0) lgkmcnt(0)
	v_pk_add_f32 v[52:53], v[52:53], v[56:57]
	v_pk_add_f32 v[60:61], v[60:61], v[64:65]
	v_pk_add_f32 v[54:55], v[54:55], v[58:59]
	v_pk_add_f32 v[62:63], v[62:63], v[66:67]
	v_pk_add_f32 v[52:53], v[52:53], v[60:61]
	v_pk_add_f32 v[54:55], v[54:55], v[62:63]
	v_pk_add_f32 v[52:53], v[52:53], v[72:73]
	v_pk_add_f32 v[54:55], v[54:55], v[74:75]
	v_mul_f32_e32 v80, 0xbfb8aa3b, v52
	v_mul_f32_e32 v81, 0xbfb8aa3b, v53
	v_mul_f32_e32 v82, 0xbfb8aa3b, v54
	v_mul_f32_e32 v83, 0xbfb8aa3b, v55
	v_exp_f32_e32 v80, v80
	v_exp_f32_e32 v81, v81
	v_exp_f32_e32 v82, v82
	v_exp_f32_e32 v83, v83
	s_nop 0
	v_add_f32_e32 v80, 1.0, v80
	v_add_f32_e32 v81, 1.0, v81
	v_add_f32_e32 v82, 1.0, v82
	v_add_f32_e32 v83, 1.0, v83
	v_rcp_f32_e32 v80, v80
	v_rcp_f32_e32 v81, v81
	v_rcp_f32_e32 v82, v82
	v_rcp_f32_e32 v83, v83
	v_lshlrev_b32_e32 v84, 16, v68
	v_and_b32_e32 v85, 0xffff0000, v68
	v_lshlrev_b32_e32 v86, 16, v69
	v_and_b32_e32 v87, 0xffff0000, v69
	v_mul_f32_e32 v80, v84, v80
	v_mul_f32_e32 v81, v85, v81
	v_mul_f32_e32 v82, v86, v82
	v_mul_f32_e32 v83, v87, v83
	v_cvt_pk_bf16_f32 v88, v80, v81
	v_cvt_pk_bf16_f32 v89, v82, v83
	global_store_dwordx2 v[76:77], v[88:89], off
.Lp5_done_p5:
	s_branch .LBB0_872
.Lp5_old_p5:
	s_cmp_gt_i32 s84, 31
	s_cbranch_scc1 .LBB0_872
	s_lshl_b32 s2, s87, 4
	v_and_b32_e32 v8, 15, v138
	s_add_i32 s2, s2, 0x8000
	v_ashrrev_i32_e32 v9, 4, v138
	v_or_b32_e32 v6, s2, v8
	v_mov_b32_e32 v7, 0
	v_lshlrev_b32_e32 v2, 3, v9
	v_lshlrev_b64 v[0:1], 10, v[6:7]
	v_ashrrev_i32_e32 v3, 31, v2
	v_lshl_add_u64 v[0:1], s[10:11], 0, v[0:1]
	v_lshlrev_b64 v[4:5], 1, v[2:3]
	v_lshlrev_b64 v[6:7], 11, v[6:7]
	v_lshl_add_u64 v[2:3], v[0:1], 0, v[4:5]
	v_lshl_add_u64 v[4:5], s[0:1], 0, v[4:5]
	v_lshlrev_b32_e32 v9, 2, v9
	v_lshl_add_u64 v[6:7], s[8:9], 0, v[6:7]
	s_lshl_b32 s0, s84, 4
	s_lshl_b32 s1, s78, 4
	s_mov_b32 s2, s84

;     DI void elem(int row, int col, const f32x4 v) const { u32x2 w; w.x = pk2(v[0], v[1]); w.y = pk2(v[2], v[3]); *(u32x2*)(y + (size_t)row * 1024 + col) = w; }
; DI f32x4 mini_acc(const bf16_t* Arow, const bf16_t* Brow, int K) {
;     f32x4 acc = (f32x4){0.f, 0.f, 0.f, 0.f};
;     int k0 = 0;
;     for (; k0 + 512 <= K; k0 += 512) { bf16x8 a[16], b[16];
; #pragma unroll
;         for (int e = 0; e < 16; ++e) { a[e] = *(const bf16x8*)(Arow + k0 + 32 * e); b[e] = *(const bf16x8*)(Brow + k0 + 32 * e); }
; #pragma unroll
;         for (int e = 0; e < 16; ++e) acc = __builtin_amdgcn_mfma_f32_16x16x32_bf16(b[e], a[e], acc, 0, 0, 0); }
; template <class Epi>
; DI void mini_gemm(const bf16_t* A, int lda, const bf16_t* Bt, int ldb, int K, int N, int acol_per_256, const Epi& E, int bx, int G, int wave, int lane) {
;     const int fr = lane & 15, fq = lane >> 4; const int row = NP + 16 * wave + fr;
;     for (int q = bx; q < N / 16; q += G) {
;         const bf16_t* Arow = A + (size_t)row * lda + ((16 * q) >> 8) * acol_per_256 + 8 * fq;
;         const bf16_t* Brow = Bt + (size_t)(16 * q + fr) * ldb + 8 * fq;
;         const f32x4 acc = mini_acc(Arow, Brow, K);
;         E.elem(row, 16 * q + 4 * fq, acc); }
.LBB0_1383:
	s_cmp_lg_u32 s78, 0x100
	s_cbranch_scc1 .Lqk_old_p11
	v_readlane_b32 s6, v254, 0
	v_readlane_b32 s7, v254, 1
	s_load_dwordx2 s[6:7], s[6:7], 0xd0
	v_mbcnt_lo_u32_b32 v0, -1, 0
	v_mbcnt_hi_u32_b32 v0, -1, v0
	v_and_b32_e32 v1, 15, v0
	v_lshrrev_b32_e32 v2, 4, v0
	s_and_b32 s32, s87, 3
	s_lshl_b32 s32, s32, 9
	v_lshl_add_u32 v6, v2, 4, s32
	v_mov_b32_e32 v7, 0
	s_add_u32 s98, s90, 0x4400000
	s_addc_u32 s99, s91, 0
	s_add_u32 s100, s90, 0x700000
	s_addc_u32 s101, s91, 0
	s_movk_i32 s2, 0x800
	s_lshl_b32 s1, s87, 10
	v_lshl_add_u32 v16, v0, 4, s1
	v_lshl_add_u64 v[14:15], s[98:99], 0, v[6:7]
	v_lshl_add_u64 v[18:19], s[100:101], 0, v[6:7]
	s_add_i32 s3, s84, 0x0
	s_and_b32 s0, s3, 7
	s_lshr_b32 s1, s3, 5
	s_lshl_b32 s1, s1, 3
	s_add_i32 s0, s0, s1
	s_bfe_u32 s1, s3, 0x20003
	s_lshl_b32 s1, s1, 1
	s_lshr_b32 s4, s87, 2
	s_add_i32 s1, s1, s4
	s_lshl_b32 s1, s1, 4
	s_add_i32 s4, s1, 0x8000
	v_add_u32_e32 v3, s4, v1
	s_lshl_b32 s4, s0, 4
	v_add_u32_e32 v4, s4, v1
	v_mad_u64_u32 v[8:9], vcc, v3, s2, v[14:15]
	v_mad_u64_u32 v[10:11], vcc, v4, s2, v[18:19]
	global_load_dwordx4 v[20:23], v[8:9], off
	global_load_dwordx4 v[52:55], v[10:11], off
	global_load_dwordx4 v[24:27], v[8:9], off offset:64
	global_load_dwordx4 v[56:59], v[10:11], off offset:64
	global_load_dwordx4 v[28:31], v[8:9], off offset:128
	global_load_dwordx4 v[60:63], v[10:11], off offset:128
	global_load_dwordx4 v[32:35], v[8:9], off offset:192
	global_load_dwordx4 v[64:67], v[10:11], off offset:192
	global_load_dwordx4 v[36:39], v[8:9], off offset:256
	global_load_dwordx4 v[68:71], v[10:11], off offset:256
	global_load_dwordx4 v[40:43], v[8:9], off offset:320
	global_load_dwordx4 v[72:75], v[10:11], off offset:320
	global_load_dwordx4 v[44:47], v[8:9], off offset:384
	global_load_dwordx4 v[76:79], v[10:11], off offset:384
	global_load_dwordx4 v[48:51], v[8:9], off offset:448
	global_load_dwordx4 v[80:83], v[10:11], off offset:448
	s_add_i32 s3, s84, 0x100
	s_and_b32 s0, s3, 7
	s_lshr_b32 s1, s3, 5
	s_lshl_b32 s1, s1, 3
	s_add_i32 s0, s0, s1
	s_bfe_u32 s1, s3, 0x20003
	s_lshl_b32 s1, s1, 1
	s_lshr_b32 s4, s87, 2
	s_add_i32 s1, s1, s4
	s_lshl_b32 s1, s1, 4
	s_add_i32 s4, s1, 0x8000
	v_add_u32_e32 v3, s4, v1
	s_lshl_b32 s4, s0, 4
	v_add_u32_e32 v4, s4, v1
	v_mad_u64_u32 v[8:9], vcc, v3, s2, v[14:15]
	v_mad_u64_u32 v[10:11], vcc, v4, s2, v[18:19]
	global_load_dwordx4 v[84:87], v[8:9], off
	global_load_dwordx4 v[116:119], v[10:11], off
	global_load_dwordx4 v[88:91], v[8:9], off offset:64
	global_load_dwordx4 v[120:123], v[10:11], off offset:64
	global_load_dwordx4 v[92:95], v[8:9], off offset:128
	global_load_dwordx4 v[124:127], v[10:11], off offset:128
	global_load_dwordx4 v[96:99], v[8:9], off offset:192
	global_load_dwordx4 v[128:131], v[10:11], off offset:192
	global_load_dwordx4 v[100:103], v[8:9], off offset:256
	global_load_dwordx4 v[132:135], v[10:11], off offset:256
	global_load_dwordx4 v[104:107], v[8:9], off offset:320
	global_load_dwordx4 v[136:139], v[10:11], off offset:320
	global_load_dwordx4 v[108:111], v[8:9], off offset:384
	global_load_dwordx4 v[140:143], v[10:11], off offset:384
	global_load_dwordx4 v[112:115], v[8:9], off offset:448
	global_load_dwordx4 v[144:147], v[10:11], off offset:448
	s_add_i32 s3, s84, 0x200
	s_and_b32 s0, s3, 7
	s_lshr_b32 s1, s3, 5
	s_lshl_b32 s1, s1, 3
	s_add_i32 s0, s0, s1
	s_bfe_u32 s1, s3, 0x20003
	s_lshl_b32 s1, s1, 1
	s_lshr_b32 s4, s87, 2
	s_add_i32 s1, s1, s4
	s_lshl_b32 s1, s1, 4
	s_add_i32 s4, s1, 0x8000
	v_add_u32_e32 v3, s4, v1
	s_lshl_b32 s4, s0, 4
	v_add_u32_e32 v4, s4, v1
	v_mad_u64_u32 v[8:9], vcc, v3, s2, v[14:15]
	v_mad_u64_u32 v[10:11], vcc, v4, s2, v[18:19]
	global_load_dwordx4 v[148:151], v[8:9], off
	global_load_dwordx4 v[180:183], v[10:11], off
	global_load_dwordx4 v[152:155], v[8:9], off offset:64
	global_load_dwordx4 v[184:187], v[10:11], off offset:64
	global_load_dwordx4 v[156:159], v[8:9], off offset:128
	global_load_dwordx4 v[188:191], v[10:11], off offset:128
	global_load_dwordx4 v[160:163], v[8:9], off offset:192
	global_load_dwordx4 v[192:195], v[10:11], off offset:192
	global_load_dwordx4 v[164:167], v[8:9], off offset:256
	global_load_dwordx4 v[196:199], v[10:11], off offset:256
	global_load_dwordx4 v[168:171], v[8:9], off offset:320
	global_load_dwordx4 v[200:203], v[10:11], off offset:320
	global_load_dwordx4 v[172:175], v[8:9], off offset:384
	global_load_dwordx4 v[204:207], v[10:11], off offset:384
	global_load_dwordx4 v[176:179], v[8:9], off offset:448
	global_load_dwordx4 v[208:211], v[10:11], off offset:448
	s_waitcnt vmcnt(46)
	v_mfma_f32_16x16x32_bf16 v[212:215], v[52:55], v[20:23], 0
	s_waitcnt vmcnt(44)
	v_mfma_f32_16x16x32_bf16 v[212:215], v[56:59], v[24:27], v[212:215]
	s_waitcnt vmcnt(42)
	v_mfma_f32_16x16x32_bf16 v[212:215], v[60:63], v[28:31], v[212:215]
	s_waitcnt vmcnt(40)
	v_mfma_f32_16x16x32_bf16 v[212:215], v[64:67], v[32:35], v[212:215]
	s_waitcnt vmcnt(38)
	v_mfma_f32_16x16x32_bf16 v[212:215], v[68:71], v[36:39], v[212:215]
	s_waitcnt vmcnt(36)
	v_mfma_f32_16x16x32_bf16 v[212:215], v[72:75], v[40:43], v[212:215]
	s_waitcnt vmcnt(34)
	v_mfma_f32_16x16x32_bf16 v[212:215], v[76:79], v[44:47], v[212:215]
	s_waitcnt vmcnt(32)
	v_mfma_f32_16x16x32_bf16 v[212:215], v[80:83], v[48:51], v[212:215]
	s_waitcnt vmcnt(30)
	v_mfma_f32_16x16x32_bf16 v[216:219], v[116:119], v[84:87], 0
	s_waitcnt vmcnt(28)
	v_mfma_f32_16x16x32_bf16 v[216:219], v[120:123], v[88:91], v[216:219]
	s_waitcnt vmcnt(26)
	v_mfma_f32_16x16x32_bf16 v[216:219], v[124:127], v[92:95], v[216:219]
	s_waitcnt vmcnt(24)
	v_mfma_f32_16x16x32_bf16 v[216:219], v[128:131], v[96:99], v[216:219]
	s_waitcnt vmcnt(22)
	v_mfma_f32_16x16x32_bf16 v[216:219], v[132:135], v[100:103], v[216:219]
	s_waitcnt vmcnt(20)
	v_mfma_f32_16x16x32_bf16 v[216:219], v[136:139], v[104:107], v[216:219]
	s_waitcnt vmcnt(18)
	v_mfma_f32_16x16x32_bf16 v[216:219], v[140:143], v[108:111], v[216:219]
	s_waitcnt vmcnt(16)
	v_mfma_f32_16x16x32_bf16 v[216:219], v[144:147], v[112:115], v[216:219]
	s_waitcnt vmcnt(14)
	v_mfma_f32_16x16x32_bf16 v[220:223], v[180:183], v[148:151], 0
	s_waitcnt vmcnt(12)
	v_mfma_f32_16x16x32_bf16 v[220:223], v[184:187], v[152:155], v[220:223]
	s_waitcnt vmcnt(10)
	v_mfma_f32_16x16x32_bf16 v[220:223], v[188:191], v[156:159], v[220:223]
	s_waitcnt vmcnt(8)
	v_mfma_f32_16x16x32_bf16 v[220:223], v[192:195], v[160:163], v[220:223]
	s_waitcnt vmcnt(6)
	v_mfma_f32_16x16x32_bf16 v[220:223], v[196:199], v[164:167], v[220:223]
	s_waitcnt vmcnt(4)
	v_mfma_f32_16x16x32_bf16 v[220:223], v[200:203], v[168:171], v[220:223]
	s_waitcnt vmcnt(2)
	v_mfma_f32_16x16x32_bf16 v[220:223], v[204:207], v[172:175], v[220:223]
	s_waitcnt vmcnt(0)
	v_mfma_f32_16x16x32_bf16 v[220:223], v[208:211], v[176:179], v[220:223]
	s_nop 7
	s_nop 1
	ds_write_b128 v16, v[212:215] offset:0
	ds_write_b128 v16, v[216:219] offset:8192
	ds_write_b128 v16, v[220:223] offset:16384
	s_waitcnt lgkmcnt(0)
	s_barrier
;     DI void elem(int row, int col, const f32x4 v) const { u32x2 w; w.x = pk2(v[0], v[1]); w.y = pk2(v[2], v[3]); *(u32x2*)(y + (size_t)row * 1024 + col) = w; }
;     DI void elem(int row, int colg, const f32x4 v) const {
;         const int which = colg >> 10, col = colg & 1023; const float sc = which == 0 ? 0.125f * 1.4426950408889634f : 1.0f;
;         u32x2 w; w.x = pk2(v[0] * sc, v[1] * sc); w.y = pk2(v[2] * sc, v[3] * sc);
;         *(u32x2*)(qkv + (size_t)which * (65 * MiB / 2) + (size_t)row * 1024 + col) = w;
;         if (which != 0) *(f32x4*)(out + (which == 1 ? O_KS : O_VS) + (size_t)(row - NP) * 1024 + col) = v; }
	s_and_b32 s1, s87, 3
	s_cmp_lg_u32 s1, 0
	s_cbranch_scc1 .Lqk_done_p11
	ds_read_b128 v[20:23], v16 offset:1024
	ds_read_b128 v[24:27], v16 offset:2048
	ds_read_b128 v[28:31], v16 offset:3072
	ds_read_b128 v[32:35], v16 offset:9216
	ds_read_b128 v[36:39], v16 offset:10240
	ds_read_b128 v[40:43], v16 offset:11264
	ds_read_b128 v[44:47], v16 offset:17408
	ds_read_b128 v[48:51], v16 offset:18432
	ds_read_b128 v[52:55], v16 offset:19456
	s_waitcnt lgkmcnt(0)
	v_pk_add_f32 v[212:213], v[212:213], v[20:21]
	v_pk_add_f32 v[24:25], v[24:25], v[28:29]
	v_pk_add_f32 v[214:215], v[214:215], v[22:23]
	v_pk_add_f32 v[26:27], v[26:27], v[30:31]
	v_pk_add_f32 v[212:213], v[212:213], v[24:25]
	v_pk_add_f32 v[214:215], v[214:215], v[26:27]
	v_pk_add_f32 v[216:217], v[216:217], v[32:33]
	v_pk_add_f32 v[36:37], v[36:37], v[40:41]
	v_pk_add_f32 v[218:219], v[218:219], v[34:35]
	v_pk_add_f32 v[38:39], v[38:39], v[42:43]
	v_pk_add_f32 v[216:217], v[216:217], v[36:37]
	v_pk_add_f32 v[218:219], v[218:219], v[38:39]
	v_pk_add_f32 v[220:221], v[220:221], v[44:45]
	v_pk_add_f32 v[48:49], v[48:49], v[52:53]
	v_pk_add_f32 v[222:223], v[222:223], v[46:47]
	v_pk_add_f32 v[50:51], v[50:51], v[54:55]
	v_pk_add_f32 v[220:221], v[220:221], v[48:49]
	v_pk_add_f32 v[222:223], v[222:223], v[50:51]
	s_waitcnt lgkmcnt(0)
	s_add_i32 s3, s84, 0x0
	s_and_b32 s0, s3, 7
	s_lshr_b32 s1, s3, 5
	s_lshl_b32 s1, s1, 3
	s_add_i32 s0, s0, s1
	s_bfe_u32 s1, s3, 0x20003
	s_lshl_b32 s1, s1, 1
	s_lshr_b32 s4, s87, 2
	s_add_i32 s1, s1, s4
	s_lshl_b32 s1, s1, 4
	s_lshr_b32 s4, s0, 6
	s_and_b32 s5, s0, 63
	s_lshl_b32 s5, s5, 4
	v_lshl_add_u32 v60, v2, 2, s5
	v_add_u32_e32 v61, s1, v1
	s_cmp_lg_u32 s4, 0
	s_cbranch_scc1 .Lqk_kv_p11_0
	v_mul_f32_e32 v64, 0x3e38aa3b, v212
	v_mul_f32_e32 v65, 0x3e38aa3b, v213
	v_mul_f32_e32 v66, 0x3e38aa3b, v214
	v_mul_f32_e32 v67, 0x3e38aa3b, v215
	s_branch .Lqk_st_p11_0
.Lqk_kv_p11_0:
	s_mov_b32 s5, 0xc29e000
	s_cmp_eq_u32 s4, 1
	s_cselect_b32 s5, 0xc21e000, s5
	s_add_u32 s8, s6, s5
	s_addc_u32 s9, s7, 0
	v_lshlrev_b32_e32 v62, 10, v61
	v_add_lshl_u32 v62, v62, v60, 2
	v_mov_b32_e32 v63, 0
	v_lshl_add_u64 v[62:63], s[8:9], 0, v[62:63]
	global_store_dwordx4 v[62:63], v[212:215], off
	v_mov_b32_e32 v64, v212
	v_mov_b32_e32 v65, v213
	v_mov_b32_e32 v66, v214
	v_mov_b32_e32 v67, v215
.Lqk_st_p11_0:
	v_cvt_pk_bf16_f32 v68, v64, v65
	v_cvt_pk_bf16_f32 v69, v66, v67
	s_mul_i32 s5, s4, 0x4100000
	s_add_u32 s8, s90, 0x14800000
	s_addc_u32 s9, s91, 0
	s_add_u32 s8, s8, s5
	s_addc_u32 s9, s9, 0
	v_add_u32_e32 v70, 0x8000, v61
	v_lshlrev_b32_e32 v72, 1, v60
	v_mov_b32_e32 v73, 0
	v_lshl_add_u64 v[72:73], s[8:9], 0, v[72:73]
	v_mad_u64_u32 v[72:73], vcc, v70, s2, v[72:73]
	global_store_dwordx2 v[72:73], v[68:69], off
	s_add_i32 s3, s84, 0x100
	s_and_b32 s0, s3, 7
	s_lshr_b32 s1, s3, 5
	s_lshl_b32 s1, s1, 3
	s_add_i32 s0, s0, s1
	s_bfe_u32 s1, s3, 0x20003
	s_lshl_b32 s1, s1, 1
	s_lshr_b32 s4, s87, 2
	s_add_i32 s1, s1, s4
	s_lshl_b32 s1, s1, 4
	s_lshr_b32 s4, s0, 6
	s_and_b32 s5, s0, 63
	s_lshl_b32 s5, s5, 4
	v_lshl_add_u32 v60, v2, 2, s5
	v_add_u32_e32 v61, s1, v1
	s_cmp_lg_u32 s4, 0
	s_cbranch_scc1 .Lqk_kv_p11_1
	v_mul_f32_e32 v64, 0x3e38aa3b, v216
	v_mul_f32_e32 v65, 0x3e38aa3b, v217
	v_mul_f32_e32 v66, 0x3e38aa3b, v218
	v_mul_f32_e32 v67, 0x3e38aa3b, v219
	s_branch .Lqk_st_p11_1
.Lqk_kv_p11_1:
	s_mov_b32 s5, 0xc29e000
	s_cmp_eq_u32 s4, 1
	s_cselect_b32 s5, 0xc21e000, s5
	s_add_u32 s8, s6, s5
	s_addc_u32 s9, s7, 0
	v_lshlrev_b32_e32 v62, 10, v61
	v_add_lshl_u32 v62, v62, v60, 2
	v_mov_b32_e32 v63, 0
	v_lshl_add_u64 v[62:63], s[8:9], 0, v[62:63]
	global_store_dwordx4 v[62:63], v[216:219], off
	v_mov_b32_e32 v64, v216
	v_mov_b32_e32 v65, v217
	v_mov_b32_e32 v66, v218
	v_mov_b32_e32 v67, v219
.Lqk_st_p11_1:
	v_cvt_pk_bf16_f32 v68, v64, v65
	v_cvt_pk_bf16_f32 v69, v66, v67
	s_mul_i32 s5, s4, 0x4100000
	s_add_u32 s8, s90, 0x14800000
	s_addc_u32 s9, s91, 0
	s_add_u32 s8, s8, s5
	s_addc_u32 s9, s9, 0
	v_add_u32_e32 v70, 0x8000, v61
	v_lshlrev_b32_e32 v72, 1, v60
	v_mov_b32_e32 v73, 0
	v_lshl_add_u64 v[72:73], s[8:9], 0, v[72:73]
	v_mad_u64_u32 v[72:73], vcc, v70, s2, v[72:73]
	global_store_dwordx2 v[72:73], v[68:69], off
	s_add_i32 s3, s84, 0x200
	s_and_b32 s0, s3, 7
	s_lshr_b32 s1, s3, 5
	s_lshl_b32 s1, s1, 3
	s_add_i32 s0, s0, s1
	s_bfe_u32 s1, s3, 0x20003
	s_lshl_b32 s1, s1, 1
	s_lshr_b32 s4, s87, 2
	s_add_i32 s1, s1, s4
	s_lshl_b32 s1, s1, 4
	s_lshr_b32 s4, s0, 6
	s_and_b32 s5, s0, 63
	s_lshl_b32 s5, s5, 4
	v_lshl_add_u32 v60, v2, 2, s5
	v_add_u32_e32 v61, s1, v1
	s_cmp_lg_u32 s4, 0
	s_cbranch_scc1 .Lqk_kv_p11_2
	v_mul_f32_e32 v64, 0x3e38aa3b, v220
	v_mul_f32_e32 v65, 0x3e38aa3b, v221
	v_mul_f32_e32 v66, 0x3e38aa3b, v222
	v_mul_f32_e32 v67, 0x3e38aa3b, v223
	s_branch .Lqk_st_p11_2
.Lqk_kv_p11_2:
	s_mov_b32 s5, 0xc29e000
	s_cmp_eq_u32 s4, 1
	s_cselect_b32 s5, 0xc21e000, s5
	s_add_u32 s8, s6, s5
	s_addc_u32 s9, s7, 0
	v_lshlrev_b32_e32 v62, 10, v61
	v_add_lshl_u32 v62, v62, v60, 2
	v_mov_b32_e32 v63, 0
	v_lshl_add_u64 v[62:63], s[8:9], 0, v[62:63]
	global_store_dwordx4 v[62:63], v[220:223], off
	v_mov_b32_e32 v64, v220
	v_mov_b32_e32 v65, v221
	v_mov_b32_e32 v66, v222
	v_mov_b32_e32 v67, v223
.Lqk_st_p11_2:
	v_cvt_pk_bf16_f32 v68, v64, v65
	v_cvt_pk_bf16_f32 v69, v66, v67
	s_mul_i32 s5, s4, 0x4100000
	s_add_u32 s8, s90, 0x14800000
	s_addc_u32 s9, s91, 0
	s_add_u32 s8, s8, s5
	s_addc_u32 s9, s9, 0
	v_add_u32_e32 v70, 0x8000, v61
	v_lshlrev_b32_e32 v72, 1, v60
	v_mov_b32_e32 v73, 0
	v_lshl_add_u64 v[72:73], s[8:9], 0, v[72:73]
	v_mad_u64_u32 v[72:73], vcc, v70, s2, v[72:73]
	global_store_dwordx2 v[72:73], v[68:69], off
.Lqk_done_p11:
	s_branch .LBB0_1388
.Lqk_old_p11:
	s_cmpk_gt_i32 s84, 0xbf
	s_cbranch_scc1 .LBB0_1388
	s_lshl_b32 s0, s87, 4
	v_and_b32_e32 v14, 15, v144
	s_add_i32 s0, s0, 0x8000
	v_ashrrev_i32_e32 v10, 4, v144
	v_or_b32_e32 v4, s0, v14
	v_mov_b32_e32 v5, 0
	v_lshlrev_b32_e32 v6, 3, v10
	v_lshlrev_b64 v[0:1], 11, v[4:5]
	v_ashrrev_i32_e32 v7, 31, v6
	v_add_u32_e32 v4, 0xffff8000, v4
	v_lshl_add_u64 v[2:3], s[20:21], 0, v[0:1]
	v_lshlrev_b64 v[8:9], 1, v[6:7]
	v_lshlrev_b32_e32 v15, 2, v10
	v_lshl_add_u64 v[10:11], s[18:19], 0, v[0:1]
	v_lshlrev_b64 v[0:1], 12, v[4:5]
	v_lshl_add_u64 v[6:7], v[2:3], 0, v[8:9]
	v_lshl_add_u64 v[8:9], s[4:5], 0, v[8:9]
	s_waitcnt lgkmcnt(0)
	v_lshl_add_u64 v[12:13], s[16:17], 0, v[0:1]
	s_lshl_b32 s2, s84, 4
	s_lshl_b32 s3, s78, 4
	s_movk_i32 s4, 0x3ff
	s_movk_i32 s5, 0x400
	v_mov_b32_e32 v16, 0x3e38aa3b
	s_mov_b32 s8, 0x4100000
	v_mov_b32_e32 v17, 0xc29e000
	v_mov_b32_e32 v18, 0xc21e000
	s_mov_b32 s9, s84
	s_branch .LBB0_1386
